# NSA fast paths specialised per current ring slot (4 copies per loop): the 8 K-tile ds_read addresses are lane-offset VGPR + immediate, 8 v_add_u32 per step removed; also SALU instead of VALU for two u
# baseline (speedup 1.0000x reference)
; #define LAS __attribute__((address_space(3)))
; DI void co_issue(const Params& P, LAS unsigned char* ring, int slot, unsigned desc, int b, int g, int wave, int lane) {
;     const int mode = (int)(desc >> 16), key_base = (int)(desc & 0xffffu);
;     const bf16_t* kb; const bf16_t* vb; unsigned ks_b, vs_b;
;     if (mode <= 1) { kb = P_kc + (size_t)(b * 2 + g) * 128 * 128; ks_b = 256u; vb = P_vcT + (size_t)(b * 2 + g) * 128 * 128; vs_b = 256u; }
;     else if (mode == 2) { kb = P_proj + (size_t)b * TT * LDP + C_KWIN + g * 128; ks_b = LDP * 2u; vb = P_vwinT + (size_t)(b * 2 + g) * 128 * TT; vs_b = TT * 2u; }
;     else { kb = P_proj + (size_t)b * TT * LDP + C_KSLC + g * 128; ks_b = LDP * 2u; vb = P_vslcT + (size_t)(b * 2 + g) * 128 * TT; vs_b = TT * 2u; }
.LBB0_417:
	s_waitcnt lgkmcnt(0)
	s_barrier
	s_add_i32 s79, s16, 2
	s_cmp_gt_i32 s79, s33
	s_cbranch_scc1 .LBB0_422
	v_mov_b32_e32 v0, s75
	ds_read_b32 v0, v0
	s_waitcnt lgkmcnt(0)
	v_readfirstlane_b32 s82, v0
	s_cmp_gt_u32 s46, s82
	s_cbranch_scc1 .LBB0_420
	s_cmp_lt_u32 s82, 0x30000
	s_cselect_b32 s0, 0x4000, s51
	s_cselect_b32 s16, s50, 0x3c800000
	s_add_u32 s4, s72, s0
	s_addc_u32 s5, s73, 0
	s_movk_i32 s83, 0x7600
	s_movk_i32 s81, 0x1000
	s_mov_b64 s[36:37], s[16:17]
	s_mov_b64 s[40:41], s[20:21]
	s_branch .LBB0_421

; #define LAS __attribute__((address_space(3)))
; DI void co_issue(const Params& P, LAS unsigned char* ring, int slot, unsigned desc, int b, int g, int wave, int lane) {
;     const int mode = (int)(desc >> 16), key_base = (int)(desc & 0xffffu);
;     const bf16_t* kb; const bf16_t* vb; unsigned ks_b, vs_b;
;     if (mode <= 1) { kb = P_kc + (size_t)(b * 2 + g) * 128 * 128; ks_b = 256u; vb = P_vcT + (size_t)(b * 2 + g) * 128 * 128; vs_b = 256u; }
;     else if (mode == 2) { kb = P_proj + (size_t)b * TT * LDP + C_KWIN + g * 128; ks_b = LDP * 2u; vb = P_vwinT + (size_t)(b * 2 + g) * 128 * TT; vs_b = TT * 2u; }
;     else { kb = P_proj + (size_t)b * TT * LDP + C_KSLC + g * 128; ks_b = LDP * 2u; vb = P_vslcT + (size_t)(b * 2 + g) * 128 * TT; vs_b = TT * 2u; }
.LBB0_446:
	s_waitcnt lgkmcnt(0)
	s_barrier
	s_add_i32 s80, s79, 2
	s_cmp_gt_i32 s80, s33
	s_cbranch_scc1 .LBB0_451
	s_add_i32 s0, s77, 0
	v_mov_b32_e32 v5, s0
	ds_read_b32 v5, v5
	s_waitcnt lgkmcnt(0)
	v_readfirstlane_b32 s82, v5
	s_cmp_gt_u32 s46, s82
	s_cbranch_scc1 .LBB0_449
	s_cmp_lt_u32 s82, 0x30000
	s_cselect_b32 s0, 0x4000, s51
	s_cselect_b32 s16, s50, 0x3c800000
	s_add_u32 s8, s73, s0
	s_addc_u32 s9, s74, 0
	s_movk_i32 s83, 0x7600
	s_movk_i32 s81, 0x1000
	s_mov_b64 s[36:37], s[16:17]
	s_mov_b64 s[40:41], s[20:21]
	s_branch .LBB0_450

; #define LAS __attribute__((address_space(3)))
; DI void co_issue(const Params& P, LAS unsigned char* ring, int slot, unsigned desc, int b, int g, int wave, int lane) {
;     const int mode = (int)(desc >> 16), key_base = (int)(desc & 0xffffu);
;     const bf16_t* kb; const bf16_t* vb; unsigned ks_b, vs_b;
;     if (mode <= 1) { kb = P_kc + (size_t)(b * 2 + g) * 128 * 128; ks_b = 256u; vb = P_vcT + (size_t)(b * 2 + g) * 128 * 128; vs_b = 256u; }
;     else if (mode == 2) { kb = P_proj + (size_t)b * TT * LDP + C_KWIN + g * 128; ks_b = LDP * 2u; vb = P_vwinT + (size_t)(b * 2 + g) * 128 * TT; vs_b = TT * 2u; }
;     else { kb = P_proj + (size_t)b * TT * LDP + C_KSLC + g * 128; ks_b = LDP * 2u; vb = P_vslcT + (size_t)(b * 2 + g) * 128 * TT; vs_b = TT * 2u; }
.LBB0_510:
	s_waitcnt lgkmcnt(0)
	s_barrier
	s_cmp_gt_i32 s77, s33
	s_cbranch_scc1 .LBB0_515
	v_readfirstlane_b32 s81, v238
	s_cmp_gt_u32 s46, s81
	s_cbranch_scc1 .LBB0_513
	s_cmp_lt_u32 s81, 0x30000
	s_cselect_b32 s0, 0x4000, s51
	s_cselect_b32 s16, s50, 0x3c800000
	s_add_u32 s2, s73, s0
	s_addc_u32 s3, s74, 0
	s_movk_i32 s82, 0x7600
	s_movk_i32 s80, 0x1000
	s_mov_b64 s[8:9], s[16:17]
	s_mov_b64 s[40:41], s[20:21]
	s_branch .LBB0_514

; #define CO_STEP2(list, n, i) do { \
;     if ((n) - 1 - (i) >= 1) asm volatile("s_waitcnt vmcnt(2)" ::: "memory"); else asm volatile("s_waitcnt vmcnt(0)" ::: "memory"); \
;     asm volatile("s_waitcnt lgkmcnt(0)" ::: "memory"); __builtin_amdgcn_s_barrier(); asm volatile("" ::: "memory"); \
;     if ((i) + 2 < (n)) co_issue(P, ring, ((i) + 2) & 3, (list)[(i) + 2], b, g, wave, lane); } while (0)
; #define CO_PIPE(MODE, REL, KB, RS) do { const bool rel_ = (REL); LAS unsigned char* sp_ = ring + (i & 3) * 16384; f32x16 Sn_; \
;     if (rel_) Sn_ = co_qk1(sp_, qf, ka); \
;     if (pend) co_finish<MODE>(Sp, pst, pkb, st, tq, prs, vb, hh); \
;     pend = rel_; if (rel_) { Sp = Sn_; pst = sp_; pkb = (KB); prs = (RS); } } while (0)
; DI void nsa_block_item(const Params& P, unsigned char* smem_g, int b, int g, int tb, int tid_in) {
;     ...
;     for (; i < n1; ++i) { CO_STEP2(list1, n1, i); const int kb_ = lo + 32 * (i - 2 * nA); CO_PIPE(2, kb_ + 31 >= t0 - 511 && kb_ <= t0 + 3, kb_, true); }
.LBB0_515:
	s_add_i32 s0, s68, 31
	s_cmp_ge_i32 s0, s71
	s_cselect_b64 s[0:1], -1, 0
	s_cmp_le_i32 s68, s72
	s_cselect_b64 s[2:3], -1, 0
	s_and_b64 s[8:9], s[0:1], s[2:3]
	s_and_b32 s16, s76, 0xc000
	s_andn2_b64 s[2:3], exec, s[8:9]
	s_andn2_b64 vcc, exec, s[8:9]
	s_add_i32 s16, s16, 0
	s_cbranch_vccnz .LBB0_517
	s_andn2_b64 vcc, exec, s[36:37]
	s_cbranch_vccnz .Lfast_win_orig
	s_add_i32 s88, s72, s79
	s_sub_i32 s88, s88, 34
	s_cmp_lt_u32 s88, 0x1de
	s_cbranch_scc1 .Lfast_win
	s_branch .Lfs_win

; #define CO_STEP2(list, n, i) do { \
;     if ((n) - 1 - (i) >= 1) asm volatile("s_waitcnt vmcnt(2)" ::: "memory"); else asm volatile("s_waitcnt vmcnt(0)" ::: "memory"); \
;     asm volatile("s_waitcnt lgkmcnt(0)" ::: "memory"); __builtin_amdgcn_s_barrier(); asm volatile("" ::: "memory"); \
;     if ((i) + 2 < (n)) co_issue(P, ring, ((i) + 2) & 3, (list)[(i) + 2], b, g, wave, lane); } while (0)
; #define CO_PIPE(MODE, REL, KB, RS) do { const bool rel_ = (REL); LAS unsigned char* sp_ = ring + (i & 3) * 16384; f32x16 Sn_; \
;     if (rel_) Sn_ = co_qk1(sp_, qf, ka); \
;     if (pend) co_finish<MODE>(Sp, pst, pkb, st, tq, prs, vb, hh); \
;     pend = rel_; if (rel_) { Sp = Sn_; pst = sp_; pkb = (KB); prs = (RS); } } while (0)
; DI void nsa_block_item(const Params& P, unsigned char* smem_g, int b, int g, int tb, int tid_in) {
;     ...
;     for (i = 0; i < n2; ++i) {
;         CO_STEP2(list2, n2, i); const int kb_ = (int)(list2[i] & 0xffffu); const int j = kb_ >> 6;
;         CO_PIPE(1, ((Uw >> j) & 1u) && kb_ <= t0 + 3, kb_, (bool)((mysel >> j) & 1u));
.Lsel_pf_ok:
	s_add_i32 s73, s41, 2
	s_cmp_ge_i32 s73, s33
	s_cbranch_scc1 .LBB0_546
	v_readfirstlane_b32 s76, v238
	s_cmp_gt_u32 s46, s76
	s_cbranch_scc1 .LBB0_544
	s_cmp_lt_u32 s76, 0x30000
	s_cselect_b32 s16, s50, 0x3c800000
	s_cselect_b32 s3, s69, s66
	s_cselect_b32 s2, s68, s63
	s_movk_i32 s77, 0x7600
	s_movk_i32 s75, 0x1000
	s_mov_b64 s[8:9], s[16:17]
	s_mov_b64 s[40:41], s[20:21]
	s_branch .LBB0_545

; #define CO_STEP2(list, n, i) do { \
;     if ((n) - 1 - (i) >= 1) asm volatile("s_waitcnt vmcnt(2)" ::: "memory"); else asm volatile("s_waitcnt vmcnt(0)" ::: "memory"); \
;     asm volatile("s_waitcnt lgkmcnt(0)" ::: "memory"); __builtin_amdgcn_s_barrier(); asm volatile("" ::: "memory"); \
;     if ((i) + 2 < (n)) co_issue(P, ring, ((i) + 2) & 3, (list)[(i) + 2], b, g, wave, lane); } while (0)
; #define CO_PIPE(MODE, REL, KB, RS) do { const bool rel_ = (REL); LAS unsigned char* sp_ = ring + (i & 3) * 16384; f32x16 Sn_; \
;     if (rel_) Sn_ = co_qk1(sp_, qf, ka); \
;     if (pend) co_finish<MODE>(Sp, pst, pkb, st, tq, prs, vb, hh); \
;     pend = rel_; if (rel_) { Sp = Sn_; pst = sp_; pkb = (KB); prs = (RS); } } while (0)
; DI void nsa_block_item(const Params& P, unsigned char* smem_g, int b, int g, int tb, int tid_in) {
;     ...
;     for (i = 0; i < n2; ++i) {
;         CO_STEP2(list2, n2, i); const int kb_ = (int)(list2[i] & 0xffffu); const int j = kb_ >> 6;
;         CO_PIPE(1, ((Uw >> j) & 1u) && kb_ <= t0 + 3, kb_, (bool)((mysel >> j) & 1u));
.LBB0_546:
	v_readfirstlane_b32 s0, v237
	s_and_b32 s16, s0, 0xffff
	s_bfe_u32 s0, s0, 0xa0006
	s_lshl_b32 s41, 1, s0
	s_and_b32 s0, s41, s70
	s_cmp_lg_u32 s0, 0
	s_cselect_b64 s[0:1], -1, 0
	s_cmp_le_i32 s16, s25
	s_cselect_b64 s[2:3], -1, 0
	s_and_b64 s[8:9], s[0:1], s[2:3]
	s_and_b32 s40, s72, 0xc000
	s_andn2_b64 s[2:3], exec, s[8:9]
	s_andn2_b64 vcc, exec, s[8:9]
	s_add_i32 s40, s40, 0
	s_cbranch_vccnz .LBB0_548
	s_andn2_b64 vcc, exec, s[36:37]
	s_cbranch_vccnz .Lfast_sel_orig
	s_add_i32 s88, s59, s74
	s_cmp_ge_i32 s88, 31
	s_cbranch_scc1 .Lfast_sel
	s_branch .Lfs_sel

; #define LAS __attribute__((address_space(3)))
; DI float xh_max(float x) { const unsigned u = __float_as_uint(x); const auto r = __builtin_amdgcn_permlane32_swap(u, u, false, false); return fmaxf(__uint_as_float(r[0]), __uint_as_float(r[1])); }
; DI float xh_sum(float x) { const unsigned u = __float_as_uint(x); const auto r = __builtin_amdgcn_permlane32_swap(u, u, false, false); return __uint_as_float(r[0]) + __uint_as_float(r[1]); }
; #define MFMA32(a, b, c) __builtin_amdgcn_mfma_f32_32x32x16_bf16((a), (b), (c), 0, 0, 0)
; DI f32x16 co_qk1(LAS unsigned char* st, const bf16x8 (&qf)[8], int ka_in) {
;     const int ka = ka_in;
;     f32x16 S;
; #pragma unroll
;     for (int i = 0; i < 16; ++i) S[i] = 0.f;
;     __builtin_amdgcn_s_setprio(1);
; #pragma unroll
;     for (int ks = 0; ks < 8; ++ks) { const bf16x8 a = *(const LAS bf16x8*)(st + (ka ^ (32 * ks))); S = MFMA32(a, qf[ks], S); }
;     __builtin_amdgcn_s_setprio(0);
;     return S;
; }
; template <int MODE>
; DI void co_finish(f32x16 S, LAS unsigned char* st, int key_base, AttnState& as, int tq, bool rowsel, int vb_in, int hh) {
;     const int vb = vb_in;
;     {
;         const int base = key_base + 4 * hh;
;         const int hi = (MODE == 0) ? (((tq - 31) >> 4) - base) : (tq - base);
;         const int lo = hi - 512;
; #pragma unroll
;         for (int i = 0; i < 16; ++i) { const int c = (i & 3) + 8 * (i >> 2); bool ok = (c <= hi); if (MODE == 2) ok = ok && (c > lo); if (MODE == 1) ok = ok && rowsel; S[i] = ok ? S[i] : -1e30f; }
;     }
;     float mx = S[0];
; #pragma unroll
;     for (int i = 1; i < 16; ++i) mx = fmaxf(mx, S[i]);
;     mx = xh_max(mx);
;     const float mxs = mx * SM_SCALE; const bool need = mxs > as.m + 8.f;
;     const float mnew = need ? mxs : as.m, muse = -fmaxf(mnew, -1e20f); float ps = 0.f;
; #pragma unroll
;     for (int i = 0; i < 16; ++i) { const float p = __builtin_amdgcn_exp2f(__builtin_fmaf(S[i], SM_SCALE, muse)); S[i] = p; ps += p; }
;     ps = xh_sum(ps);
;     if (__builtin_amdgcn_ballot_w64(need) != 0ull) {
;         const float alpha = __builtin_amdgcn_exp2f(as.m - mnew);
;         as.l *= alpha;
; #pragma unroll
;         for (int dt = 0; dt < 4; ++dt)
; #pragma unroll
;             for (int i = 0; i < 16; ++i) as.acc[dt][i] *= alpha;
;     }
;     as.l += ps; as.m = mnew;
.Lfast_sel:
	s_lshr_b32 s88, s40, 14
	s_cmp_eq_u32 s88, 0
	s_cbranch_scc1 .Lfast_sel_s0
	s_cmp_eq_u32 s88, 1
	s_cbranch_scc1 .Lfast_sel_s1
	s_cmp_eq_u32 s88, 2
	s_cbranch_scc1 .Lfast_sel_s2
	s_branch .Lfast_sel_s3
.Lfast_sel_s0:
	ds_read_b128 v[216:219], v162
	ds_read_b128 v[220:223], v164
	ds_read_b128 v[224:227], v165
	ds_read_b128 v[228:231], v166
	ds_read_b128 v[232:235], v167
	ds_read_b128 v[240:243], v168
	ds_read_b128 v[244:247], v169
	ds_read_b128 v[248:251], v170
	v_max_f32_e32 v0, v16, v17
	v_max3_f32 v0, v0, v18, v19
	v_max3_f32 v0, v0, v20, v21
	v_max3_f32 v0, v0, v22, v23
	s_waitcnt lgkmcnt(7)
	v_mfma_f32_32x32x16_bf16 v[96:111], v[216:219], v[112:115], 0
	v_max3_f32 v0, v0, v24, v25
	v_max3_f32 v0, v0, v26, v27
	v_max3_f32 v0, v0, v28, v29
	v_max3_f32 v0, v0, v30, v31
	v_mov_b32_e32 v15, v0
	v_add_u32_e32 v253, s62, v156
	v_add_u32_e32 v254, s62, v171
	v_permlane32_swap_b32_e32 v0, v15
	ds_read_b64 v[180:181], v253 offset:8192
	ds_read_b64 v[182:183], v254 offset:8192
	ds_read_b64 v[184:185], v253 offset:10240
	ds_read_b64 v[186:187], v254 offset:10240
	ds_read_b64 v[188:189], v253 offset:12288
	ds_read_b64 v[190:191], v254 offset:12288
	ds_read_b64 v[192:193], v253 offset:14336
	ds_read_b64 v[194:195], v254 offset:14336
	v_max_f32_e32 v0, v0, v15
	s_waitcnt lgkmcnt(14)
	v_mfma_f32_32x32x16_bf16 v[96:111], v[220:223], v[116:119], v[96:111]
	v_cndmask_b32_e64 v0, v153, v0, s[26:27]
	v_mul_f32_e32 v0, 0x3e0293ee, v0
	v_add_f32_e32 v15, 0x41000000, v175
	v_cmp_gt_f32_e32 vcc, v0, v15
	v_add_u32_e32 v255, s62, v172
	v_add_u32_e32 v214, s62, v173
	v_cndmask_b32_e32 v174, v175, v0, vcc
	v_max_f32_e32 v14, 0xe0ad78ec, v174
	v_mov_b32_e32 v13, 0x7149f2ca
	v_cndmask_b32_e64 v14, v13, v14, s[26:27]
	s_waitcnt lgkmcnt(13)
	v_mfma_f32_32x32x16_bf16 v[96:111], v[224:227], v[120:123], v[96:111]
	s_cbranch_vccz .Lfast_sel_nr_s0
	v_sub_f32_e32 v175, v175, v174
	v_exp_f32_e32 v12, v175
	s_nop 0
	v_mul_f32_e32 v163, v163, v12
	v_pk_mul_f32 v[94:95], v[94:95], v[12:13] op_sel_hi:[1,0]
	v_pk_mul_f32 v[92:93], v[92:93], v[12:13] op_sel_hi:[1,0]
	v_pk_mul_f32 v[90:91], v[90:91], v[12:13] op_sel_hi:[1,0]
	v_pk_mul_f32 v[88:89], v[88:89], v[12:13] op_sel_hi:[1,0]
	v_pk_mul_f32 v[86:87], v[86:87], v[12:13] op_sel_hi:[1,0]
	v_pk_mul_f32 v[84:85], v[84:85], v[12:13] op_sel_hi:[1,0]
	v_pk_mul_f32 v[82:83], v[82:83], v[12:13] op_sel_hi:[1,0]
	v_pk_mul_f32 v[80:81], v[80:81], v[12:13] op_sel_hi:[1,0]
	v_pk_mul_f32 v[78:79], v[78:79], v[12:13] op_sel_hi:[1,0]
	v_pk_mul_f32 v[76:77], v[76:77], v[12:13] op_sel_hi:[1,0]
	v_pk_mul_f32 v[74:75], v[74:75], v[12:13] op_sel_hi:[1,0]
	v_pk_mul_f32 v[72:73], v[72:73], v[12:13] op_sel_hi:[1,0]
	v_pk_mul_f32 v[70:71], v[70:71], v[12:13] op_sel_hi:[1,0]
	v_pk_mul_f32 v[68:69], v[68:69], v[12:13] op_sel_hi:[1,0]
	v_pk_mul_f32 v[66:67], v[66:67], v[12:13] op_sel_hi:[1,0]
	v_pk_mul_f32 v[64:65], v[64:65], v[12:13] op_sel_hi:[1,0]
	v_pk_mul_f32 v[62:63], v[62:63], v[12:13] op_sel_hi:[1,0]
	v_pk_mul_f32 v[60:61], v[60:61], v[12:13] op_sel_hi:[1,0]
	v_pk_mul_f32 v[58:59], v[58:59], v[12:13] op_sel_hi:[1,0]
	v_pk_mul_f32 v[56:57], v[56:57], v[12:13] op_sel_hi:[1,0]
	v_pk_mul_f32 v[54:55], v[54:55], v[12:13] op_sel_hi:[1,0]
	v_pk_mul_f32 v[52:53], v[52:53], v[12:13] op_sel_hi:[1,0]
	v_pk_mul_f32 v[50:51], v[50:51], v[12:13] op_sel_hi:[1,0]
	v_pk_mul_f32 v[48:49], v[48:49], v[12:13] op_sel_hi:[1,0]
	v_pk_mul_f32 v[46:47], v[46:47], v[12:13] op_sel_hi:[1,0]
	v_pk_mul_f32 v[44:45], v[44:45], v[12:13] op_sel_hi:[1,0]
	v_pk_mul_f32 v[42:43], v[42:43], v[12:13] op_sel_hi:[1,0]
	v_pk_mul_f32 v[40:41], v[40:41], v[12:13] op_sel_hi:[1,0]
	v_pk_mul_f32 v[38:39], v[38:39], v[12:13] op_sel_hi:[1,0]
	v_pk_mul_f32 v[36:37], v[36:37], v[12:13] op_sel_hi:[1,0]
	v_pk_mul_f32 v[34:35], v[34:35], v[12:13] op_sel_hi:[1,0]
	v_pk_mul_f32 v[32:33], v[32:33], v[12:13] op_sel_hi:[1,0]

; #define LAS __attribute__((address_space(3)))
; DI float xh_max(float x) { const unsigned u = __float_as_uint(x); const auto r = __builtin_amdgcn_permlane32_swap(u, u, false, false); return fmaxf(__uint_as_float(r[0]), __uint_as_float(r[1])); }
; DI float xh_sum(float x) { const unsigned u = __float_as_uint(x); const auto r = __builtin_amdgcn_permlane32_swap(u, u, false, false); return __uint_as_float(r[0]) + __uint_as_float(r[1]); }
; #define MFMA32(a, b, c) __builtin_amdgcn_mfma_f32_32x32x16_bf16((a), (b), (c), 0, 0, 0)
; DI f32x16 co_qk1(LAS unsigned char* st, const bf16x8 (&qf)[8], int ka_in) {
;     const int ka = ka_in;
;     f32x16 S;
; #pragma unroll
;     for (int i = 0; i < 16; ++i) S[i] = 0.f;
;     __builtin_amdgcn_s_setprio(1);
; #pragma unroll
;     for (int ks = 0; ks < 8; ++ks) { const bf16x8 a = *(const LAS bf16x8*)(st + (ka ^ (32 * ks))); S = MFMA32(a, qf[ks], S); }
;     __builtin_amdgcn_s_setprio(0);
;     return S;
; }
; template <int MODE>
; DI void co_finish(f32x16 S, LAS unsigned char* st, int key_base, AttnState& as, int tq, bool rowsel, int vb_in, int hh) {
;     const int vb = vb_in;
;     {
;         const int base = key_base + 4 * hh;
;         const int hi = (MODE == 0) ? (((tq - 31) >> 4) - base) : (tq - base);
;         const int lo = hi - 512;
; #pragma unroll
;         for (int i = 0; i < 16; ++i) { const int c = (i & 3) + 8 * (i >> 2); bool ok = (c <= hi); if (MODE == 2) ok = ok && (c > lo); if (MODE == 1) ok = ok && rowsel; S[i] = ok ? S[i] : -1e30f; }
;     }
;     float mx = S[0];
; #pragma unroll
;     for (int i = 1; i < 16; ++i) mx = fmaxf(mx, S[i]);
;     mx = xh_max(mx);
;     const float mxs = mx * SM_SCALE; const bool need = mxs > as.m + 8.f;
;     const float mnew = need ? mxs : as.m, muse = -fmaxf(mnew, -1e20f); float ps = 0.f;
; #pragma unroll
;     for (int i = 0; i < 16; ++i) { const float p = __builtin_amdgcn_exp2f(__builtin_fmaf(S[i], SM_SCALE, muse)); S[i] = p; ps += p; }
;     ps = xh_sum(ps);
;     if (__builtin_amdgcn_ballot_w64(need) != 0ull) {
;         const float alpha = __builtin_amdgcn_exp2f(as.m - mnew);
;         as.l *= alpha;
; #pragma unroll
;         for (int dt = 0; dt < 4; ++dt)
; #pragma unroll
;             for (int i = 0; i < 16; ++i) as.acc[dt][i] *= alpha;
;     }
;     as.l += ps; as.m = mnew;
.Lfast_sel_s1:
	ds_read_b128 v[216:219], v162 offset:16384
	ds_read_b128 v[220:223], v164 offset:16384
	ds_read_b128 v[224:227], v165 offset:16384
	ds_read_b128 v[228:231], v166 offset:16384
	ds_read_b128 v[232:235], v167 offset:16384
	ds_read_b128 v[240:243], v168 offset:16384
	ds_read_b128 v[244:247], v169 offset:16384
	ds_read_b128 v[248:251], v170 offset:16384
	v_max_f32_e32 v0, v16, v17
	v_max3_f32 v0, v0, v18, v19
	v_max3_f32 v0, v0, v20, v21
	v_max3_f32 v0, v0, v22, v23
	s_waitcnt lgkmcnt(7)
	v_mfma_f32_32x32x16_bf16 v[96:111], v[216:219], v[112:115], 0
	v_max3_f32 v0, v0, v24, v25
	v_max3_f32 v0, v0, v26, v27
	v_max3_f32 v0, v0, v28, v29
	v_max3_f32 v0, v0, v30, v31
	v_mov_b32_e32 v15, v0
	v_add_u32_e32 v253, s62, v156
	v_add_u32_e32 v254, s62, v171
	v_permlane32_swap_b32_e32 v0, v15
	ds_read_b64 v[180:181], v253 offset:8192
	ds_read_b64 v[182:183], v254 offset:8192
	ds_read_b64 v[184:185], v253 offset:10240
	ds_read_b64 v[186:187], v254 offset:10240
	ds_read_b64 v[188:189], v253 offset:12288
	ds_read_b64 v[190:191], v254 offset:12288
	ds_read_b64 v[192:193], v253 offset:14336
	ds_read_b64 v[194:195], v254 offset:14336
	v_max_f32_e32 v0, v0, v15
	s_waitcnt lgkmcnt(14)
	v_mfma_f32_32x32x16_bf16 v[96:111], v[220:223], v[116:119], v[96:111]
	v_cndmask_b32_e64 v0, v153, v0, s[26:27]
	v_mul_f32_e32 v0, 0x3e0293ee, v0
	v_add_f32_e32 v15, 0x41000000, v175
	v_cmp_gt_f32_e32 vcc, v0, v15
	v_add_u32_e32 v255, s62, v172
	v_add_u32_e32 v214, s62, v173
	v_cndmask_b32_e32 v174, v175, v0, vcc
	v_max_f32_e32 v14, 0xe0ad78ec, v174
	v_mov_b32_e32 v13, 0x7149f2ca
	v_cndmask_b32_e64 v14, v13, v14, s[26:27]
	s_waitcnt lgkmcnt(13)
	v_mfma_f32_32x32x16_bf16 v[96:111], v[224:227], v[120:123], v[96:111]
	s_cbranch_vccz .Lfast_sel_nr_s1
	v_sub_f32_e32 v175, v175, v174
	v_exp_f32_e32 v12, v175
	s_nop 0
	v_mul_f32_e32 v163, v163, v12
	v_pk_mul_f32 v[94:95], v[94:95], v[12:13] op_sel_hi:[1,0]
	v_pk_mul_f32 v[92:93], v[92:93], v[12:13] op_sel_hi:[1,0]
	v_pk_mul_f32 v[90:91], v[90:91], v[12:13] op_sel_hi:[1,0]
	v_pk_mul_f32 v[88:89], v[88:89], v[12:13] op_sel_hi:[1,0]
	v_pk_mul_f32 v[86:87], v[86:87], v[12:13] op_sel_hi:[1,0]
	v_pk_mul_f32 v[84:85], v[84:85], v[12:13] op_sel_hi:[1,0]
	v_pk_mul_f32 v[82:83], v[82:83], v[12:13] op_sel_hi:[1,0]
	v_pk_mul_f32 v[80:81], v[80:81], v[12:13] op_sel_hi:[1,0]
	v_pk_mul_f32 v[78:79], v[78:79], v[12:13] op_sel_hi:[1,0]
	v_pk_mul_f32 v[76:77], v[76:77], v[12:13] op_sel_hi:[1,0]
	v_pk_mul_f32 v[74:75], v[74:75], v[12:13] op_sel_hi:[1,0]
	v_pk_mul_f32 v[72:73], v[72:73], v[12:13] op_sel_hi:[1,0]
	v_pk_mul_f32 v[70:71], v[70:71], v[12:13] op_sel_hi:[1,0]
	v_pk_mul_f32 v[68:69], v[68:69], v[12:13] op_sel_hi:[1,0]
	v_pk_mul_f32 v[66:67], v[66:67], v[12:13] op_sel_hi:[1,0]
	v_pk_mul_f32 v[64:65], v[64:65], v[12:13] op_sel_hi:[1,0]
	v_pk_mul_f32 v[62:63], v[62:63], v[12:13] op_sel_hi:[1,0]
	v_pk_mul_f32 v[60:61], v[60:61], v[12:13] op_sel_hi:[1,0]
	v_pk_mul_f32 v[58:59], v[58:59], v[12:13] op_sel_hi:[1,0]
	v_pk_mul_f32 v[56:57], v[56:57], v[12:13] op_sel_hi:[1,0]
	v_pk_mul_f32 v[54:55], v[54:55], v[12:13] op_sel_hi:[1,0]
	v_pk_mul_f32 v[52:53], v[52:53], v[12:13] op_sel_hi:[1,0]
	v_pk_mul_f32 v[50:51], v[50:51], v[12:13] op_sel_hi:[1,0]
	v_pk_mul_f32 v[48:49], v[48:49], v[12:13] op_sel_hi:[1,0]
	v_pk_mul_f32 v[46:47], v[46:47], v[12:13] op_sel_hi:[1,0]
	v_pk_mul_f32 v[44:45], v[44:45], v[12:13] op_sel_hi:[1,0]
	v_pk_mul_f32 v[42:43], v[42:43], v[12:13] op_sel_hi:[1,0]
	v_pk_mul_f32 v[40:41], v[40:41], v[12:13] op_sel_hi:[1,0]
	v_pk_mul_f32 v[38:39], v[38:39], v[12:13] op_sel_hi:[1,0]
	v_pk_mul_f32 v[36:37], v[36:37], v[12:13] op_sel_hi:[1,0]
	v_pk_mul_f32 v[34:35], v[34:35], v[12:13] op_sel_hi:[1,0]
	v_pk_mul_f32 v[32:33], v[32:33], v[12:13] op_sel_hi:[1,0]

; #define LAS __attribute__((address_space(3)))
; DI float xh_max(float x) { const unsigned u = __float_as_uint(x); const auto r = __builtin_amdgcn_permlane32_swap(u, u, false, false); return fmaxf(__uint_as_float(r[0]), __uint_as_float(r[1])); }
; DI float xh_sum(float x) { const unsigned u = __float_as_uint(x); const auto r = __builtin_amdgcn_permlane32_swap(u, u, false, false); return __uint_as_float(r[0]) + __uint_as_float(r[1]); }
; #define MFMA32(a, b, c) __builtin_amdgcn_mfma_f32_32x32x16_bf16((a), (b), (c), 0, 0, 0)
; DI f32x16 co_qk1(LAS unsigned char* st, const bf16x8 (&qf)[8], int ka_in) {
;     const int ka = ka_in;
;     f32x16 S;
; #pragma unroll
;     for (int i = 0; i < 16; ++i) S[i] = 0.f;
;     __builtin_amdgcn_s_setprio(1);
; #pragma unroll
;     for (int ks = 0; ks < 8; ++ks) { const bf16x8 a = *(const LAS bf16x8*)(st + (ka ^ (32 * ks))); S = MFMA32(a, qf[ks], S); }
;     __builtin_amdgcn_s_setprio(0);
;     return S;
; }
; template <int MODE>
; DI void co_finish(f32x16 S, LAS unsigned char* st, int key_base, AttnState& as, int tq, bool rowsel, int vb_in, int hh) {
;     const int vb = vb_in;
;     {
;         const int base = key_base + 4 * hh;
;         const int hi = (MODE == 0) ? (((tq - 31) >> 4) - base) : (tq - base);
;         const int lo = hi - 512;
; #pragma unroll
;         for (int i = 0; i < 16; ++i) { const int c = (i & 3) + 8 * (i >> 2); bool ok = (c <= hi); if (MODE == 2) ok = ok && (c > lo); if (MODE == 1) ok = ok && rowsel; S[i] = ok ? S[i] : -1e30f; }
;     }
;     float mx = S[0];
; #pragma unroll
;     for (int i = 1; i < 16; ++i) mx = fmaxf(mx, S[i]);
;     mx = xh_max(mx);
;     const float mxs = mx * SM_SCALE; const bool need = mxs > as.m + 8.f;
;     const float mnew = need ? mxs : as.m, muse = -fmaxf(mnew, -1e20f); float ps = 0.f;
; #pragma unroll
;     for (int i = 0; i < 16; ++i) { const float p = __builtin_amdgcn_exp2f(__builtin_fmaf(S[i], SM_SCALE, muse)); S[i] = p; ps += p; }
;     ps = xh_sum(ps);
;     if (__builtin_amdgcn_ballot_w64(need) != 0ull) {
;         const float alpha = __builtin_amdgcn_exp2f(as.m - mnew);
;         as.l *= alpha;
; #pragma unroll
;         for (int dt = 0; dt < 4; ++dt)
; #pragma unroll
;             for (int i = 0; i < 16; ++i) as.acc[dt][i] *= alpha;
;     }
;     as.l += ps; as.m = mnew;
.Lfast_sel_s2:
	ds_read_b128 v[216:219], v162 offset:32768
	ds_read_b128 v[220:223], v164 offset:32768
	ds_read_b128 v[224:227], v165 offset:32768
	ds_read_b128 v[228:231], v166 offset:32768
	ds_read_b128 v[232:235], v167 offset:32768
	ds_read_b128 v[240:243], v168 offset:32768
	ds_read_b128 v[244:247], v169 offset:32768
	ds_read_b128 v[248:251], v170 offset:32768
	v_max_f32_e32 v0, v16, v17
	v_max3_f32 v0, v0, v18, v19
	v_max3_f32 v0, v0, v20, v21
	v_max3_f32 v0, v0, v22, v23
	s_waitcnt lgkmcnt(7)
	v_mfma_f32_32x32x16_bf16 v[96:111], v[216:219], v[112:115], 0
	v_max3_f32 v0, v0, v24, v25
	v_max3_f32 v0, v0, v26, v27
	v_max3_f32 v0, v0, v28, v29
	v_max3_f32 v0, v0, v30, v31
	v_mov_b32_e32 v15, v0
	v_add_u32_e32 v253, s62, v156
	v_add_u32_e32 v254, s62, v171
	v_permlane32_swap_b32_e32 v0, v15
	ds_read_b64 v[180:181], v253 offset:8192
	ds_read_b64 v[182:183], v254 offset:8192
	ds_read_b64 v[184:185], v253 offset:10240
	ds_read_b64 v[186:187], v254 offset:10240
	ds_read_b64 v[188:189], v253 offset:12288
	ds_read_b64 v[190:191], v254 offset:12288
	ds_read_b64 v[192:193], v253 offset:14336
	ds_read_b64 v[194:195], v254 offset:14336
	v_max_f32_e32 v0, v0, v15
	s_waitcnt lgkmcnt(14)
	v_mfma_f32_32x32x16_bf16 v[96:111], v[220:223], v[116:119], v[96:111]
	v_cndmask_b32_e64 v0, v153, v0, s[26:27]
	v_mul_f32_e32 v0, 0x3e0293ee, v0
	v_add_f32_e32 v15, 0x41000000, v175
	v_cmp_gt_f32_e32 vcc, v0, v15
	v_add_u32_e32 v255, s62, v172
	v_add_u32_e32 v214, s62, v173
	v_cndmask_b32_e32 v174, v175, v0, vcc
	v_max_f32_e32 v14, 0xe0ad78ec, v174
	v_mov_b32_e32 v13, 0x7149f2ca
	v_cndmask_b32_e64 v14, v13, v14, s[26:27]
	s_waitcnt lgkmcnt(13)
	v_mfma_f32_32x32x16_bf16 v[96:111], v[224:227], v[120:123], v[96:111]
	s_cbranch_vccz .Lfast_sel_nr_s2
	v_sub_f32_e32 v175, v175, v174
	v_exp_f32_e32 v12, v175
	s_nop 0
	v_mul_f32_e32 v163, v163, v12
	v_pk_mul_f32 v[94:95], v[94:95], v[12:13] op_sel_hi:[1,0]
	v_pk_mul_f32 v[92:93], v[92:93], v[12:13] op_sel_hi:[1,0]
	v_pk_mul_f32 v[90:91], v[90:91], v[12:13] op_sel_hi:[1,0]
	v_pk_mul_f32 v[88:89], v[88:89], v[12:13] op_sel_hi:[1,0]
	v_pk_mul_f32 v[86:87], v[86:87], v[12:13] op_sel_hi:[1,0]
	v_pk_mul_f32 v[84:85], v[84:85], v[12:13] op_sel_hi:[1,0]
	v_pk_mul_f32 v[82:83], v[82:83], v[12:13] op_sel_hi:[1,0]
	v_pk_mul_f32 v[80:81], v[80:81], v[12:13] op_sel_hi:[1,0]
	v_pk_mul_f32 v[78:79], v[78:79], v[12:13] op_sel_hi:[1,0]
	v_pk_mul_f32 v[76:77], v[76:77], v[12:13] op_sel_hi:[1,0]
	v_pk_mul_f32 v[74:75], v[74:75], v[12:13] op_sel_hi:[1,0]
	v_pk_mul_f32 v[72:73], v[72:73], v[12:13] op_sel_hi:[1,0]
	v_pk_mul_f32 v[70:71], v[70:71], v[12:13] op_sel_hi:[1,0]
	v_pk_mul_f32 v[68:69], v[68:69], v[12:13] op_sel_hi:[1,0]
	v_pk_mul_f32 v[66:67], v[66:67], v[12:13] op_sel_hi:[1,0]
	v_pk_mul_f32 v[64:65], v[64:65], v[12:13] op_sel_hi:[1,0]
	v_pk_mul_f32 v[62:63], v[62:63], v[12:13] op_sel_hi:[1,0]
	v_pk_mul_f32 v[60:61], v[60:61], v[12:13] op_sel_hi:[1,0]
	v_pk_mul_f32 v[58:59], v[58:59], v[12:13] op_sel_hi:[1,0]
	v_pk_mul_f32 v[56:57], v[56:57], v[12:13] op_sel_hi:[1,0]
	v_pk_mul_f32 v[54:55], v[54:55], v[12:13] op_sel_hi:[1,0]
	v_pk_mul_f32 v[52:53], v[52:53], v[12:13] op_sel_hi:[1,0]
	v_pk_mul_f32 v[50:51], v[50:51], v[12:13] op_sel_hi:[1,0]
	v_pk_mul_f32 v[48:49], v[48:49], v[12:13] op_sel_hi:[1,0]
	v_pk_mul_f32 v[46:47], v[46:47], v[12:13] op_sel_hi:[1,0]
	v_pk_mul_f32 v[44:45], v[44:45], v[12:13] op_sel_hi:[1,0]
	v_pk_mul_f32 v[42:43], v[42:43], v[12:13] op_sel_hi:[1,0]
	v_pk_mul_f32 v[40:41], v[40:41], v[12:13] op_sel_hi:[1,0]
	v_pk_mul_f32 v[38:39], v[38:39], v[12:13] op_sel_hi:[1,0]
	v_pk_mul_f32 v[36:37], v[36:37], v[12:13] op_sel_hi:[1,0]
	v_pk_mul_f32 v[34:35], v[34:35], v[12:13] op_sel_hi:[1,0]
	v_pk_mul_f32 v[32:33], v[32:33], v[12:13] op_sel_hi:[1,0]

; #define LAS __attribute__((address_space(3)))
; DI float xh_max(float x) { const unsigned u = __float_as_uint(x); const auto r = __builtin_amdgcn_permlane32_swap(u, u, false, false); return fmaxf(__uint_as_float(r[0]), __uint_as_float(r[1])); }
; DI float xh_sum(float x) { const unsigned u = __float_as_uint(x); const auto r = __builtin_amdgcn_permlane32_swap(u, u, false, false); return __uint_as_float(r[0]) + __uint_as_float(r[1]); }
; #define MFMA32(a, b, c) __builtin_amdgcn_mfma_f32_32x32x16_bf16((a), (b), (c), 0, 0, 0)
; DI f32x16 co_qk1(LAS unsigned char* st, const bf16x8 (&qf)[8], int ka_in) {
;     const int ka = ka_in;
;     f32x16 S;
; #pragma unroll
;     for (int i = 0; i < 16; ++i) S[i] = 0.f;
;     __builtin_amdgcn_s_setprio(1);
; #pragma unroll
;     for (int ks = 0; ks < 8; ++ks) { const bf16x8 a = *(const LAS bf16x8*)(st + (ka ^ (32 * ks))); S = MFMA32(a, qf[ks], S); }
;     __builtin_amdgcn_s_setprio(0);
;     return S;
; }
; template <int MODE>
; DI void co_finish(f32x16 S, LAS unsigned char* st, int key_base, AttnState& as, int tq, bool rowsel, int vb_in, int hh) {
;     const int vb = vb_in;
;     {
;         const int base = key_base + 4 * hh;
;         const int hi = (MODE == 0) ? (((tq - 31) >> 4) - base) : (tq - base);
;         const int lo = hi - 512;
; #pragma unroll
;         for (int i = 0; i < 16; ++i) { const int c = (i & 3) + 8 * (i >> 2); bool ok = (c <= hi); if (MODE == 2) ok = ok && (c > lo); if (MODE == 1) ok = ok && rowsel; S[i] = ok ? S[i] : -1e30f; }
;     }
;     float mx = S[0];
; #pragma unroll
;     for (int i = 1; i < 16; ++i) mx = fmaxf(mx, S[i]);
;     mx = xh_max(mx);
;     const float mxs = mx * SM_SCALE; const bool need = mxs > as.m + 8.f;
;     const float mnew = need ? mxs : as.m, muse = -fmaxf(mnew, -1e20f); float ps = 0.f;
; #pragma unroll
;     for (int i = 0; i < 16; ++i) { const float p = __builtin_amdgcn_exp2f(__builtin_fmaf(S[i], SM_SCALE, muse)); S[i] = p; ps += p; }
;     ps = xh_sum(ps);
;     if (__builtin_amdgcn_ballot_w64(need) != 0ull) {
;         const float alpha = __builtin_amdgcn_exp2f(as.m - mnew);
;         as.l *= alpha;
; #pragma unroll
;         for (int dt = 0; dt < 4; ++dt)
; #pragma unroll
;             for (int i = 0; i < 16; ++i) as.acc[dt][i] *= alpha;
;     }
;     as.l += ps; as.m = mnew;
.Lfast_sel_s3:
	ds_read_b128 v[216:219], v162 offset:49152
	ds_read_b128 v[220:223], v164 offset:49152
	ds_read_b128 v[224:227], v165 offset:49152
	ds_read_b128 v[228:231], v166 offset:49152
	ds_read_b128 v[232:235], v167 offset:49152
	ds_read_b128 v[240:243], v168 offset:49152
	ds_read_b128 v[244:247], v169 offset:49152
	ds_read_b128 v[248:251], v170 offset:49152
	v_max_f32_e32 v0, v16, v17
	v_max3_f32 v0, v0, v18, v19
	v_max3_f32 v0, v0, v20, v21
	v_max3_f32 v0, v0, v22, v23
	s_waitcnt lgkmcnt(7)
	v_mfma_f32_32x32x16_bf16 v[96:111], v[216:219], v[112:115], 0
	v_max3_f32 v0, v0, v24, v25
	v_max3_f32 v0, v0, v26, v27
	v_max3_f32 v0, v0, v28, v29
	v_max3_f32 v0, v0, v30, v31
	v_mov_b32_e32 v15, v0
	v_add_u32_e32 v253, s62, v156
	v_add_u32_e32 v254, s62, v171
	v_permlane32_swap_b32_e32 v0, v15
	ds_read_b64 v[180:181], v253 offset:8192
	ds_read_b64 v[182:183], v254 offset:8192
	ds_read_b64 v[184:185], v253 offset:10240
	ds_read_b64 v[186:187], v254 offset:10240
	ds_read_b64 v[188:189], v253 offset:12288
	ds_read_b64 v[190:191], v254 offset:12288
	ds_read_b64 v[192:193], v253 offset:14336
	ds_read_b64 v[194:195], v254 offset:14336
	v_max_f32_e32 v0, v0, v15
	s_waitcnt lgkmcnt(14)
	v_mfma_f32_32x32x16_bf16 v[96:111], v[220:223], v[116:119], v[96:111]
	v_cndmask_b32_e64 v0, v153, v0, s[26:27]
	v_mul_f32_e32 v0, 0x3e0293ee, v0
	v_add_f32_e32 v15, 0x41000000, v175
	v_cmp_gt_f32_e32 vcc, v0, v15
	v_add_u32_e32 v255, s62, v172
	v_add_u32_e32 v214, s62, v173
	v_cndmask_b32_e32 v174, v175, v0, vcc
	v_max_f32_e32 v14, 0xe0ad78ec, v174
	v_mov_b32_e32 v13, 0x7149f2ca
	v_cndmask_b32_e64 v14, v13, v14, s[26:27]
	s_waitcnt lgkmcnt(13)
	v_mfma_f32_32x32x16_bf16 v[96:111], v[224:227], v[120:123], v[96:111]
	s_cbranch_vccz .Lfast_sel_nr_s3
	v_sub_f32_e32 v175, v175, v174
	v_exp_f32_e32 v12, v175
	s_nop 0
	v_mul_f32_e32 v163, v163, v12
	v_pk_mul_f32 v[94:95], v[94:95], v[12:13] op_sel_hi:[1,0]
	v_pk_mul_f32 v[92:93], v[92:93], v[12:13] op_sel_hi:[1,0]
	v_pk_mul_f32 v[90:91], v[90:91], v[12:13] op_sel_hi:[1,0]
	v_pk_mul_f32 v[88:89], v[88:89], v[12:13] op_sel_hi:[1,0]
	v_pk_mul_f32 v[86:87], v[86:87], v[12:13] op_sel_hi:[1,0]
	v_pk_mul_f32 v[84:85], v[84:85], v[12:13] op_sel_hi:[1,0]
	v_pk_mul_f32 v[82:83], v[82:83], v[12:13] op_sel_hi:[1,0]
	v_pk_mul_f32 v[80:81], v[80:81], v[12:13] op_sel_hi:[1,0]
	v_pk_mul_f32 v[78:79], v[78:79], v[12:13] op_sel_hi:[1,0]
	v_pk_mul_f32 v[76:77], v[76:77], v[12:13] op_sel_hi:[1,0]
	v_pk_mul_f32 v[74:75], v[74:75], v[12:13] op_sel_hi:[1,0]
	v_pk_mul_f32 v[72:73], v[72:73], v[12:13] op_sel_hi:[1,0]
	v_pk_mul_f32 v[70:71], v[70:71], v[12:13] op_sel_hi:[1,0]
	v_pk_mul_f32 v[68:69], v[68:69], v[12:13] op_sel_hi:[1,0]
	v_pk_mul_f32 v[66:67], v[66:67], v[12:13] op_sel_hi:[1,0]
	v_pk_mul_f32 v[64:65], v[64:65], v[12:13] op_sel_hi:[1,0]
	v_pk_mul_f32 v[62:63], v[62:63], v[12:13] op_sel_hi:[1,0]
	v_pk_mul_f32 v[60:61], v[60:61], v[12:13] op_sel_hi:[1,0]
	v_pk_mul_f32 v[58:59], v[58:59], v[12:13] op_sel_hi:[1,0]
	v_pk_mul_f32 v[56:57], v[56:57], v[12:13] op_sel_hi:[1,0]
	v_pk_mul_f32 v[54:55], v[54:55], v[12:13] op_sel_hi:[1,0]
	v_pk_mul_f32 v[52:53], v[52:53], v[12:13] op_sel_hi:[1,0]
	v_pk_mul_f32 v[50:51], v[50:51], v[12:13] op_sel_hi:[1,0]
	v_pk_mul_f32 v[48:49], v[48:49], v[12:13] op_sel_hi:[1,0]
	v_pk_mul_f32 v[46:47], v[46:47], v[12:13] op_sel_hi:[1,0]
	v_pk_mul_f32 v[44:45], v[44:45], v[12:13] op_sel_hi:[1,0]
	v_pk_mul_f32 v[42:43], v[42:43], v[12:13] op_sel_hi:[1,0]
	v_pk_mul_f32 v[40:41], v[40:41], v[12:13] op_sel_hi:[1,0]
	v_pk_mul_f32 v[38:39], v[38:39], v[12:13] op_sel_hi:[1,0]
	v_pk_mul_f32 v[36:37], v[36:37], v[12:13] op_sel_hi:[1,0]
	v_pk_mul_f32 v[34:35], v[34:35], v[12:13] op_sel_hi:[1,0]
	v_pk_mul_f32 v[32:33], v[32:33], v[12:13] op_sel_hi:[1,0]

; #define LAS __attribute__((address_space(3)))
; DI float xh_max(float x) { const unsigned u = __float_as_uint(x); const auto r = __builtin_amdgcn_permlane32_swap(u, u, false, false); return fmaxf(__uint_as_float(r[0]), __uint_as_float(r[1])); }
; DI float xh_sum(float x) { const unsigned u = __float_as_uint(x); const auto r = __builtin_amdgcn_permlane32_swap(u, u, false, false); return __uint_as_float(r[0]) + __uint_as_float(r[1]); }
; #define MFMA32(a, b, c) __builtin_amdgcn_mfma_f32_32x32x16_bf16((a), (b), (c), 0, 0, 0)
; DI f32x16 co_qk1(LAS unsigned char* st, const bf16x8 (&qf)[8], int ka_in) {
;     const int ka = ka_in;
;     f32x16 S;
; #pragma unroll
;     for (int i = 0; i < 16; ++i) S[i] = 0.f;
;     __builtin_amdgcn_s_setprio(1);
; #pragma unroll
;     for (int ks = 0; ks < 8; ++ks) { const bf16x8 a = *(const LAS bf16x8*)(st + (ka ^ (32 * ks))); S = MFMA32(a, qf[ks], S); }
;     __builtin_amdgcn_s_setprio(0);
;     return S;
; }
; template <int MODE>
; DI void co_finish(f32x16 S, LAS unsigned char* st, int key_base, AttnState& as, int tq, bool rowsel, int vb_in, int hh) {
;     const int vb = vb_in;
;     {
;         const int base = key_base + 4 * hh;
;         const int hi = (MODE == 0) ? (((tq - 31) >> 4) - base) : (tq - base);
;         const int lo = hi - 512;
; #pragma unroll
;         for (int i = 0; i < 16; ++i) { const int c = (i & 3) + 8 * (i >> 2); bool ok = (c <= hi); if (MODE == 2) ok = ok && (c > lo); if (MODE == 1) ok = ok && rowsel; S[i] = ok ? S[i] : -1e30f; }
;     }
;     float mx = S[0];
; #pragma unroll
;     for (int i = 1; i < 16; ++i) mx = fmaxf(mx, S[i]);
;     mx = xh_max(mx);
;     const float mxs = mx * SM_SCALE; const bool need = mxs > as.m + 8.f;
;     const float mnew = need ? mxs : as.m, muse = -fmaxf(mnew, -1e20f); float ps = 0.f;
; #pragma unroll
;     for (int i = 0; i < 16; ++i) { const float p = __builtin_amdgcn_exp2f(__builtin_fmaf(S[i], SM_SCALE, muse)); S[i] = p; ps += p; }
;     ps = xh_sum(ps);
;     if (__builtin_amdgcn_ballot_w64(need) != 0ull) {
;         const float alpha = __builtin_amdgcn_exp2f(as.m - mnew);
;         as.l *= alpha;
; #pragma unroll
;         for (int dt = 0; dt < 4; ++dt)
; #pragma unroll
;             for (int i = 0; i < 16; ++i) as.acc[dt][i] *= alpha;
;     }
;     as.l += ps; as.m = mnew;
.Lfast_win:
	s_lshr_b32 s88, s16, 14
	s_cmp_eq_u32 s88, 0
	s_cbranch_scc1 .Lfast_win_s0
	s_cmp_eq_u32 s88, 1
	s_cbranch_scc1 .Lfast_win_s1
	s_cmp_eq_u32 s88, 2
	s_cbranch_scc1 .Lfast_win_s2
	s_branch .Lfast_win_s3
.Lfast_win_s0:
	ds_read_b128 v[216:219], v162
	ds_read_b128 v[220:223], v164
	ds_read_b128 v[224:227], v165
	ds_read_b128 v[228:231], v166
	ds_read_b128 v[232:235], v167
	ds_read_b128 v[240:243], v168
	ds_read_b128 v[244:247], v169
	ds_read_b128 v[248:251], v170
	v_max_f32_e32 v0, v16, v17
	v_max3_f32 v0, v0, v18, v19
	v_max3_f32 v0, v0, v20, v21
	v_max3_f32 v0, v0, v22, v23
	s_waitcnt lgkmcnt(7)
	v_mfma_f32_32x32x16_bf16 v[96:111], v[216:219], v[112:115], 0
	v_max3_f32 v0, v0, v24, v25
	v_max3_f32 v0, v0, v26, v27
	v_max3_f32 v0, v0, v28, v29
	v_max3_f32 v0, v0, v30, v31
	v_mov_b32_e32 v15, v0
	v_add_u32_e32 v253, s62, v156
	v_add_u32_e32 v254, s62, v171
	v_permlane32_swap_b32_e32 v0, v15
	ds_read_b64 v[180:181], v253 offset:8192
	ds_read_b64 v[182:183], v254 offset:8192
	ds_read_b64 v[184:185], v253 offset:10240
	ds_read_b64 v[186:187], v254 offset:10240
	ds_read_b64 v[188:189], v253 offset:12288
	ds_read_b64 v[190:191], v254 offset:12288
	ds_read_b64 v[192:193], v253 offset:14336
	ds_read_b64 v[194:195], v254 offset:14336
	v_max_f32_e32 v0, v0, v15
	s_waitcnt lgkmcnt(14)
	v_mfma_f32_32x32x16_bf16 v[96:111], v[220:223], v[116:119], v[96:111]
	v_mul_f32_e32 v0, 0x3e0293ee, v0
	v_add_f32_e32 v15, 0x41000000, v177
	v_cmp_gt_f32_e32 vcc, v0, v15
	v_add_u32_e32 v255, s62, v172
	v_add_u32_e32 v214, s62, v173
	v_cndmask_b32_e32 v176, v177, v0, vcc
	v_max_f32_e32 v14, 0xe0ad78ec, v176
	s_waitcnt lgkmcnt(13)
	v_mfma_f32_32x32x16_bf16 v[96:111], v[224:227], v[120:123], v[96:111]
	s_cbranch_vccz .Lfast_win_nr_s0
	v_sub_f32_e32 v177, v177, v176
	v_exp_f32_e32 v12, v177
	s_nop 0
	v_mul_f32_e32 v175, v175, v12
	v_pk_mul_f32 v[94:95], v[94:95], v[12:13] op_sel_hi:[1,0]
	v_pk_mul_f32 v[92:93], v[92:93], v[12:13] op_sel_hi:[1,0]
	v_pk_mul_f32 v[90:91], v[90:91], v[12:13] op_sel_hi:[1,0]
	v_pk_mul_f32 v[88:89], v[88:89], v[12:13] op_sel_hi:[1,0]
	v_pk_mul_f32 v[86:87], v[86:87], v[12:13] op_sel_hi:[1,0]
	v_pk_mul_f32 v[84:85], v[84:85], v[12:13] op_sel_hi:[1,0]
	v_pk_mul_f32 v[82:83], v[82:83], v[12:13] op_sel_hi:[1,0]
	v_pk_mul_f32 v[80:81], v[80:81], v[12:13] op_sel_hi:[1,0]
	v_pk_mul_f32 v[78:79], v[78:79], v[12:13] op_sel_hi:[1,0]
	v_pk_mul_f32 v[76:77], v[76:77], v[12:13] op_sel_hi:[1,0]
	v_pk_mul_f32 v[74:75], v[74:75], v[12:13] op_sel_hi:[1,0]
	v_pk_mul_f32 v[72:73], v[72:73], v[12:13] op_sel_hi:[1,0]
	v_pk_mul_f32 v[70:71], v[70:71], v[12:13] op_sel_hi:[1,0]
	v_pk_mul_f32 v[68:69], v[68:69], v[12:13] op_sel_hi:[1,0]
	v_pk_mul_f32 v[66:67], v[66:67], v[12:13] op_sel_hi:[1,0]
	v_pk_mul_f32 v[64:65], v[64:65], v[12:13] op_sel_hi:[1,0]
	v_pk_mul_f32 v[62:63], v[62:63], v[12:13] op_sel_hi:[1,0]
	v_pk_mul_f32 v[60:61], v[60:61], v[12:13] op_sel_hi:[1,0]
	v_pk_mul_f32 v[58:59], v[58:59], v[12:13] op_sel_hi:[1,0]
	v_pk_mul_f32 v[56:57], v[56:57], v[12:13] op_sel_hi:[1,0]
	v_pk_mul_f32 v[54:55], v[54:55], v[12:13] op_sel_hi:[1,0]
	v_pk_mul_f32 v[52:53], v[52:53], v[12:13] op_sel_hi:[1,0]
	v_pk_mul_f32 v[50:51], v[50:51], v[12:13] op_sel_hi:[1,0]
	v_pk_mul_f32 v[48:49], v[48:49], v[12:13] op_sel_hi:[1,0]
	v_pk_mul_f32 v[46:47], v[46:47], v[12:13] op_sel_hi:[1,0]
	v_pk_mul_f32 v[44:45], v[44:45], v[12:13] op_sel_hi:[1,0]
	v_pk_mul_f32 v[42:43], v[42:43], v[12:13] op_sel_hi:[1,0]
	v_pk_mul_f32 v[40:41], v[40:41], v[12:13] op_sel_hi:[1,0]
	v_pk_mul_f32 v[38:39], v[38:39], v[12:13] op_sel_hi:[1,0]
	v_pk_mul_f32 v[36:37], v[36:37], v[12:13] op_sel_hi:[1,0]
	v_pk_mul_f32 v[34:35], v[34:35], v[12:13] op_sel_hi:[1,0]
	v_pk_mul_f32 v[32:33], v[32:33], v[12:13] op_sel_hi:[1,0]

; #define LAS __attribute__((address_space(3)))
; DI float xh_max(float x) { const unsigned u = __float_as_uint(x); const auto r = __builtin_amdgcn_permlane32_swap(u, u, false, false); return fmaxf(__uint_as_float(r[0]), __uint_as_float(r[1])); }
; DI float xh_sum(float x) { const unsigned u = __float_as_uint(x); const auto r = __builtin_amdgcn_permlane32_swap(u, u, false, false); return __uint_as_float(r[0]) + __uint_as_float(r[1]); }
; #define MFMA32(a, b, c) __builtin_amdgcn_mfma_f32_32x32x16_bf16((a), (b), (c), 0, 0, 0)
; DI f32x16 co_qk1(LAS unsigned char* st, const bf16x8 (&qf)[8], int ka_in) {
;     const int ka = ka_in;
;     f32x16 S;
; #pragma unroll
;     for (int i = 0; i < 16; ++i) S[i] = 0.f;
;     __builtin_amdgcn_s_setprio(1);
; #pragma unroll
;     for (int ks = 0; ks < 8; ++ks) { const bf16x8 a = *(const LAS bf16x8*)(st + (ka ^ (32 * ks))); S = MFMA32(a, qf[ks], S); }
;     __builtin_amdgcn_s_setprio(0);
;     return S;
; }
; template <int MODE>
; DI void co_finish(f32x16 S, LAS unsigned char* st, int key_base, AttnState& as, int tq, bool rowsel, int vb_in, int hh) {
;     const int vb = vb_in;
;     {
;         const int base = key_base + 4 * hh;
;         const int hi = (MODE == 0) ? (((tq - 31) >> 4) - base) : (tq - base);
;         const int lo = hi - 512;
; #pragma unroll
;         for (int i = 0; i < 16; ++i) { const int c = (i & 3) + 8 * (i >> 2); bool ok = (c <= hi); if (MODE == 2) ok = ok && (c > lo); if (MODE == 1) ok = ok && rowsel; S[i] = ok ? S[i] : -1e30f; }
;     }
;     float mx = S[0];
; #pragma unroll
;     for (int i = 1; i < 16; ++i) mx = fmaxf(mx, S[i]);
;     mx = xh_max(mx);
;     const float mxs = mx * SM_SCALE; const bool need = mxs > as.m + 8.f;
;     const float mnew = need ? mxs : as.m, muse = -fmaxf(mnew, -1e20f); float ps = 0.f;
; #pragma unroll
;     for (int i = 0; i < 16; ++i) { const float p = __builtin_amdgcn_exp2f(__builtin_fmaf(S[i], SM_SCALE, muse)); S[i] = p; ps += p; }
;     ps = xh_sum(ps);
;     if (__builtin_amdgcn_ballot_w64(need) != 0ull) {
;         const float alpha = __builtin_amdgcn_exp2f(as.m - mnew);
;         as.l *= alpha;
; #pragma unroll
;         for (int dt = 0; dt < 4; ++dt)
; #pragma unroll
;             for (int i = 0; i < 16; ++i) as.acc[dt][i] *= alpha;
;     }
;     as.l += ps; as.m = mnew;
.Lfast_win_s1:
	ds_read_b128 v[216:219], v162 offset:16384
	ds_read_b128 v[220:223], v164 offset:16384
	ds_read_b128 v[224:227], v165 offset:16384
	ds_read_b128 v[228:231], v166 offset:16384
	ds_read_b128 v[232:235], v167 offset:16384
	ds_read_b128 v[240:243], v168 offset:16384
	ds_read_b128 v[244:247], v169 offset:16384
	ds_read_b128 v[248:251], v170 offset:16384
	v_max_f32_e32 v0, v16, v17
	v_max3_f32 v0, v0, v18, v19
	v_max3_f32 v0, v0, v20, v21
	v_max3_f32 v0, v0, v22, v23
	s_waitcnt lgkmcnt(7)
	v_mfma_f32_32x32x16_bf16 v[96:111], v[216:219], v[112:115], 0
	v_max3_f32 v0, v0, v24, v25
	v_max3_f32 v0, v0, v26, v27
	v_max3_f32 v0, v0, v28, v29
	v_max3_f32 v0, v0, v30, v31
	v_mov_b32_e32 v15, v0
	v_add_u32_e32 v253, s62, v156
	v_add_u32_e32 v254, s62, v171
	v_permlane32_swap_b32_e32 v0, v15
	ds_read_b64 v[180:181], v253 offset:8192
	ds_read_b64 v[182:183], v254 offset:8192
	ds_read_b64 v[184:185], v253 offset:10240
	ds_read_b64 v[186:187], v254 offset:10240
	ds_read_b64 v[188:189], v253 offset:12288
	ds_read_b64 v[190:191], v254 offset:12288
	ds_read_b64 v[192:193], v253 offset:14336
	ds_read_b64 v[194:195], v254 offset:14336
	v_max_f32_e32 v0, v0, v15
	s_waitcnt lgkmcnt(14)
	v_mfma_f32_32x32x16_bf16 v[96:111], v[220:223], v[116:119], v[96:111]
	v_mul_f32_e32 v0, 0x3e0293ee, v0
	v_add_f32_e32 v15, 0x41000000, v177
	v_cmp_gt_f32_e32 vcc, v0, v15
	v_add_u32_e32 v255, s62, v172
	v_add_u32_e32 v214, s62, v173
	v_cndmask_b32_e32 v176, v177, v0, vcc
	v_max_f32_e32 v14, 0xe0ad78ec, v176
	s_waitcnt lgkmcnt(13)
	v_mfma_f32_32x32x16_bf16 v[96:111], v[224:227], v[120:123], v[96:111]
	s_cbranch_vccz .Lfast_win_nr_s1
	v_sub_f32_e32 v177, v177, v176
	v_exp_f32_e32 v12, v177
	s_nop 0
	v_mul_f32_e32 v175, v175, v12
	v_pk_mul_f32 v[94:95], v[94:95], v[12:13] op_sel_hi:[1,0]
	v_pk_mul_f32 v[92:93], v[92:93], v[12:13] op_sel_hi:[1,0]
	v_pk_mul_f32 v[90:91], v[90:91], v[12:13] op_sel_hi:[1,0]
	v_pk_mul_f32 v[88:89], v[88:89], v[12:13] op_sel_hi:[1,0]
	v_pk_mul_f32 v[86:87], v[86:87], v[12:13] op_sel_hi:[1,0]
	v_pk_mul_f32 v[84:85], v[84:85], v[12:13] op_sel_hi:[1,0]
	v_pk_mul_f32 v[82:83], v[82:83], v[12:13] op_sel_hi:[1,0]
	v_pk_mul_f32 v[80:81], v[80:81], v[12:13] op_sel_hi:[1,0]
	v_pk_mul_f32 v[78:79], v[78:79], v[12:13] op_sel_hi:[1,0]
	v_pk_mul_f32 v[76:77], v[76:77], v[12:13] op_sel_hi:[1,0]
	v_pk_mul_f32 v[74:75], v[74:75], v[12:13] op_sel_hi:[1,0]
	v_pk_mul_f32 v[72:73], v[72:73], v[12:13] op_sel_hi:[1,0]
	v_pk_mul_f32 v[70:71], v[70:71], v[12:13] op_sel_hi:[1,0]
	v_pk_mul_f32 v[68:69], v[68:69], v[12:13] op_sel_hi:[1,0]
	v_pk_mul_f32 v[66:67], v[66:67], v[12:13] op_sel_hi:[1,0]
	v_pk_mul_f32 v[64:65], v[64:65], v[12:13] op_sel_hi:[1,0]
	v_pk_mul_f32 v[62:63], v[62:63], v[12:13] op_sel_hi:[1,0]
	v_pk_mul_f32 v[60:61], v[60:61], v[12:13] op_sel_hi:[1,0]
	v_pk_mul_f32 v[58:59], v[58:59], v[12:13] op_sel_hi:[1,0]
	v_pk_mul_f32 v[56:57], v[56:57], v[12:13] op_sel_hi:[1,0]
	v_pk_mul_f32 v[54:55], v[54:55], v[12:13] op_sel_hi:[1,0]
	v_pk_mul_f32 v[52:53], v[52:53], v[12:13] op_sel_hi:[1,0]
	v_pk_mul_f32 v[50:51], v[50:51], v[12:13] op_sel_hi:[1,0]
	v_pk_mul_f32 v[48:49], v[48:49], v[12:13] op_sel_hi:[1,0]
	v_pk_mul_f32 v[46:47], v[46:47], v[12:13] op_sel_hi:[1,0]
	v_pk_mul_f32 v[44:45], v[44:45], v[12:13] op_sel_hi:[1,0]
	v_pk_mul_f32 v[42:43], v[42:43], v[12:13] op_sel_hi:[1,0]
	v_pk_mul_f32 v[40:41], v[40:41], v[12:13] op_sel_hi:[1,0]
	v_pk_mul_f32 v[38:39], v[38:39], v[12:13] op_sel_hi:[1,0]
	v_pk_mul_f32 v[36:37], v[36:37], v[12:13] op_sel_hi:[1,0]
	v_pk_mul_f32 v[34:35], v[34:35], v[12:13] op_sel_hi:[1,0]
	v_pk_mul_f32 v[32:33], v[32:33], v[12:13] op_sel_hi:[1,0]

; #define LAS __attribute__((address_space(3)))
; DI float xh_max(float x) { const unsigned u = __float_as_uint(x); const auto r = __builtin_amdgcn_permlane32_swap(u, u, false, false); return fmaxf(__uint_as_float(r[0]), __uint_as_float(r[1])); }
; DI float xh_sum(float x) { const unsigned u = __float_as_uint(x); const auto r = __builtin_amdgcn_permlane32_swap(u, u, false, false); return __uint_as_float(r[0]) + __uint_as_float(r[1]); }
; #define MFMA32(a, b, c) __builtin_amdgcn_mfma_f32_32x32x16_bf16((a), (b), (c), 0, 0, 0)
; DI f32x16 co_qk1(LAS unsigned char* st, const bf16x8 (&qf)[8], int ka_in) {
;     const int ka = ka_in;
;     f32x16 S;
; #pragma unroll
;     for (int i = 0; i < 16; ++i) S[i] = 0.f;
;     __builtin_amdgcn_s_setprio(1);
; #pragma unroll
;     for (int ks = 0; ks < 8; ++ks) { const bf16x8 a = *(const LAS bf16x8*)(st + (ka ^ (32 * ks))); S = MFMA32(a, qf[ks], S); }
;     __builtin_amdgcn_s_setprio(0);
;     return S;
; }
; template <int MODE>
; DI void co_finish(f32x16 S, LAS unsigned char* st, int key_base, AttnState& as, int tq, bool rowsel, int vb_in, int hh) {
;     const int vb = vb_in;
;     {
;         const int base = key_base + 4 * hh;
;         const int hi = (MODE == 0) ? (((tq - 31) >> 4) - base) : (tq - base);
;         const int lo = hi - 512;
; #pragma unroll
;         for (int i = 0; i < 16; ++i) { const int c = (i & 3) + 8 * (i >> 2); bool ok = (c <= hi); if (MODE == 2) ok = ok && (c > lo); if (MODE == 1) ok = ok && rowsel; S[i] = ok ? S[i] : -1e30f; }
;     }
;     float mx = S[0];
; #pragma unroll
;     for (int i = 1; i < 16; ++i) mx = fmaxf(mx, S[i]);
;     mx = xh_max(mx);
;     const float mxs = mx * SM_SCALE; const bool need = mxs > as.m + 8.f;
;     const float mnew = need ? mxs : as.m, muse = -fmaxf(mnew, -1e20f); float ps = 0.f;
; #pragma unroll
;     for (int i = 0; i < 16; ++i) { const float p = __builtin_amdgcn_exp2f(__builtin_fmaf(S[i], SM_SCALE, muse)); S[i] = p; ps += p; }
;     ps = xh_sum(ps);
;     if (__builtin_amdgcn_ballot_w64(need) != 0ull) {
;         const float alpha = __builtin_amdgcn_exp2f(as.m - mnew);
;         as.l *= alpha;
; #pragma unroll
;         for (int dt = 0; dt < 4; ++dt)
; #pragma unroll
;             for (int i = 0; i < 16; ++i) as.acc[dt][i] *= alpha;
;     }
;     as.l += ps; as.m = mnew;
.Lfast_win_s2:
	ds_read_b128 v[216:219], v162 offset:32768
	ds_read_b128 v[220:223], v164 offset:32768
	ds_read_b128 v[224:227], v165 offset:32768
	ds_read_b128 v[228:231], v166 offset:32768
	ds_read_b128 v[232:235], v167 offset:32768
	ds_read_b128 v[240:243], v168 offset:32768
	ds_read_b128 v[244:247], v169 offset:32768
	ds_read_b128 v[248:251], v170 offset:32768
	v_max_f32_e32 v0, v16, v17
	v_max3_f32 v0, v0, v18, v19
	v_max3_f32 v0, v0, v20, v21
	v_max3_f32 v0, v0, v22, v23
	s_waitcnt lgkmcnt(7)
	v_mfma_f32_32x32x16_bf16 v[96:111], v[216:219], v[112:115], 0
	v_max3_f32 v0, v0, v24, v25
	v_max3_f32 v0, v0, v26, v27
	v_max3_f32 v0, v0, v28, v29
	v_max3_f32 v0, v0, v30, v31
	v_mov_b32_e32 v15, v0
	v_add_u32_e32 v253, s62, v156
	v_add_u32_e32 v254, s62, v171
	v_permlane32_swap_b32_e32 v0, v15
	ds_read_b64 v[180:181], v253 offset:8192
	ds_read_b64 v[182:183], v254 offset:8192
	ds_read_b64 v[184:185], v253 offset:10240
	ds_read_b64 v[186:187], v254 offset:10240
	ds_read_b64 v[188:189], v253 offset:12288
	ds_read_b64 v[190:191], v254 offset:12288
	ds_read_b64 v[192:193], v253 offset:14336
	ds_read_b64 v[194:195], v254 offset:14336
	v_max_f32_e32 v0, v0, v15
	s_waitcnt lgkmcnt(14)
	v_mfma_f32_32x32x16_bf16 v[96:111], v[220:223], v[116:119], v[96:111]
	v_mul_f32_e32 v0, 0x3e0293ee, v0
	v_add_f32_e32 v15, 0x41000000, v177
	v_cmp_gt_f32_e32 vcc, v0, v15
	v_add_u32_e32 v255, s62, v172
	v_add_u32_e32 v214, s62, v173
	v_cndmask_b32_e32 v176, v177, v0, vcc
	v_max_f32_e32 v14, 0xe0ad78ec, v176
	s_waitcnt lgkmcnt(13)
	v_mfma_f32_32x32x16_bf16 v[96:111], v[224:227], v[120:123], v[96:111]
	s_cbranch_vccz .Lfast_win_nr_s2
	v_sub_f32_e32 v177, v177, v176
	v_exp_f32_e32 v12, v177
	s_nop 0
	v_mul_f32_e32 v175, v175, v12
	v_pk_mul_f32 v[94:95], v[94:95], v[12:13] op_sel_hi:[1,0]
	v_pk_mul_f32 v[92:93], v[92:93], v[12:13] op_sel_hi:[1,0]
	v_pk_mul_f32 v[90:91], v[90:91], v[12:13] op_sel_hi:[1,0]
	v_pk_mul_f32 v[88:89], v[88:89], v[12:13] op_sel_hi:[1,0]
	v_pk_mul_f32 v[86:87], v[86:87], v[12:13] op_sel_hi:[1,0]
	v_pk_mul_f32 v[84:85], v[84:85], v[12:13] op_sel_hi:[1,0]
	v_pk_mul_f32 v[82:83], v[82:83], v[12:13] op_sel_hi:[1,0]
	v_pk_mul_f32 v[80:81], v[80:81], v[12:13] op_sel_hi:[1,0]
	v_pk_mul_f32 v[78:79], v[78:79], v[12:13] op_sel_hi:[1,0]
	v_pk_mul_f32 v[76:77], v[76:77], v[12:13] op_sel_hi:[1,0]
	v_pk_mul_f32 v[74:75], v[74:75], v[12:13] op_sel_hi:[1,0]
	v_pk_mul_f32 v[72:73], v[72:73], v[12:13] op_sel_hi:[1,0]
	v_pk_mul_f32 v[70:71], v[70:71], v[12:13] op_sel_hi:[1,0]
	v_pk_mul_f32 v[68:69], v[68:69], v[12:13] op_sel_hi:[1,0]
	v_pk_mul_f32 v[66:67], v[66:67], v[12:13] op_sel_hi:[1,0]
	v_pk_mul_f32 v[64:65], v[64:65], v[12:13] op_sel_hi:[1,0]
	v_pk_mul_f32 v[62:63], v[62:63], v[12:13] op_sel_hi:[1,0]
	v_pk_mul_f32 v[60:61], v[60:61], v[12:13] op_sel_hi:[1,0]
	v_pk_mul_f32 v[58:59], v[58:59], v[12:13] op_sel_hi:[1,0]
	v_pk_mul_f32 v[56:57], v[56:57], v[12:13] op_sel_hi:[1,0]
	v_pk_mul_f32 v[54:55], v[54:55], v[12:13] op_sel_hi:[1,0]
	v_pk_mul_f32 v[52:53], v[52:53], v[12:13] op_sel_hi:[1,0]
	v_pk_mul_f32 v[50:51], v[50:51], v[12:13] op_sel_hi:[1,0]
	v_pk_mul_f32 v[48:49], v[48:49], v[12:13] op_sel_hi:[1,0]
	v_pk_mul_f32 v[46:47], v[46:47], v[12:13] op_sel_hi:[1,0]
	v_pk_mul_f32 v[44:45], v[44:45], v[12:13] op_sel_hi:[1,0]
	v_pk_mul_f32 v[42:43], v[42:43], v[12:13] op_sel_hi:[1,0]
	v_pk_mul_f32 v[40:41], v[40:41], v[12:13] op_sel_hi:[1,0]
	v_pk_mul_f32 v[38:39], v[38:39], v[12:13] op_sel_hi:[1,0]
	v_pk_mul_f32 v[36:37], v[36:37], v[12:13] op_sel_hi:[1,0]
	v_pk_mul_f32 v[34:35], v[34:35], v[12:13] op_sel_hi:[1,0]
	v_pk_mul_f32 v[32:33], v[32:33], v[12:13] op_sel_hi:[1,0]

; #define LAS __attribute__((address_space(3)))
; DI float xh_max(float x) { const unsigned u = __float_as_uint(x); const auto r = __builtin_amdgcn_permlane32_swap(u, u, false, false); return fmaxf(__uint_as_float(r[0]), __uint_as_float(r[1])); }
; DI float xh_sum(float x) { const unsigned u = __float_as_uint(x); const auto r = __builtin_amdgcn_permlane32_swap(u, u, false, false); return __uint_as_float(r[0]) + __uint_as_float(r[1]); }
; #define MFMA32(a, b, c) __builtin_amdgcn_mfma_f32_32x32x16_bf16((a), (b), (c), 0, 0, 0)
; DI f32x16 co_qk1(LAS unsigned char* st, const bf16x8 (&qf)[8], int ka_in) {
;     const int ka = ka_in;
;     f32x16 S;
; #pragma unroll
;     for (int i = 0; i < 16; ++i) S[i] = 0.f;
;     __builtin_amdgcn_s_setprio(1);
; #pragma unroll
;     for (int ks = 0; ks < 8; ++ks) { const bf16x8 a = *(const LAS bf16x8*)(st + (ka ^ (32 * ks))); S = MFMA32(a, qf[ks], S); }
;     __builtin_amdgcn_s_setprio(0);
;     return S;
; }
; template <int MODE>
; DI void co_finish(f32x16 S, LAS unsigned char* st, int key_base, AttnState& as, int tq, bool rowsel, int vb_in, int hh) {
;     const int vb = vb_in;
;     {
;         const int base = key_base + 4 * hh;
;         const int hi = (MODE == 0) ? (((tq - 31) >> 4) - base) : (tq - base);
;         const int lo = hi - 512;
; #pragma unroll
;         for (int i = 0; i < 16; ++i) { const int c = (i & 3) + 8 * (i >> 2); bool ok = (c <= hi); if (MODE == 2) ok = ok && (c > lo); if (MODE == 1) ok = ok && rowsel; S[i] = ok ? S[i] : -1e30f; }
;     }
;     float mx = S[0];
; #pragma unroll
;     for (int i = 1; i < 16; ++i) mx = fmaxf(mx, S[i]);
;     mx = xh_max(mx);
;     const float mxs = mx * SM_SCALE; const bool need = mxs > as.m + 8.f;
;     const float mnew = need ? mxs : as.m, muse = -fmaxf(mnew, -1e20f); float ps = 0.f;
; #pragma unroll
;     for (int i = 0; i < 16; ++i) { const float p = __builtin_amdgcn_exp2f(__builtin_fmaf(S[i], SM_SCALE, muse)); S[i] = p; ps += p; }
;     ps = xh_sum(ps);
;     if (__builtin_amdgcn_ballot_w64(need) != 0ull) {
;         const float alpha = __builtin_amdgcn_exp2f(as.m - mnew);
;         as.l *= alpha;
; #pragma unroll
;         for (int dt = 0; dt < 4; ++dt)
; #pragma unroll
;             for (int i = 0; i < 16; ++i) as.acc[dt][i] *= alpha;
;     }
;     as.l += ps; as.m = mnew;
.Lfast_win_s3:
	ds_read_b128 v[216:219], v162 offset:49152
	ds_read_b128 v[220:223], v164 offset:49152
	ds_read_b128 v[224:227], v165 offset:49152
	ds_read_b128 v[228:231], v166 offset:49152
	ds_read_b128 v[232:235], v167 offset:49152
	ds_read_b128 v[240:243], v168 offset:49152
	ds_read_b128 v[244:247], v169 offset:49152
	ds_read_b128 v[248:251], v170 offset:49152
	v_max_f32_e32 v0, v16, v17
	v_max3_f32 v0, v0, v18, v19
	v_max3_f32 v0, v0, v20, v21
	v_max3_f32 v0, v0, v22, v23
	s_waitcnt lgkmcnt(7)
	v_mfma_f32_32x32x16_bf16 v[96:111], v[216:219], v[112:115], 0
	v_max3_f32 v0, v0, v24, v25
	v_max3_f32 v0, v0, v26, v27
	v_max3_f32 v0, v0, v28, v29
	v_max3_f32 v0, v0, v30, v31
	v_mov_b32_e32 v15, v0
	v_add_u32_e32 v253, s62, v156
	v_add_u32_e32 v254, s62, v171
	v_permlane32_swap_b32_e32 v0, v15
	ds_read_b64 v[180:181], v253 offset:8192
	ds_read_b64 v[182:183], v254 offset:8192
	ds_read_b64 v[184:185], v253 offset:10240
	ds_read_b64 v[186:187], v254 offset:10240
	ds_read_b64 v[188:189], v253 offset:12288
	ds_read_b64 v[190:191], v254 offset:12288
	ds_read_b64 v[192:193], v253 offset:14336
	ds_read_b64 v[194:195], v254 offset:14336
	v_max_f32_e32 v0, v0, v15
	s_waitcnt lgkmcnt(14)
	v_mfma_f32_32x32x16_bf16 v[96:111], v[220:223], v[116:119], v[96:111]
	v_mul_f32_e32 v0, 0x3e0293ee, v0
	v_add_f32_e32 v15, 0x41000000, v177
	v_cmp_gt_f32_e32 vcc, v0, v15
	v_add_u32_e32 v255, s62, v172
	v_add_u32_e32 v214, s62, v173
	v_cndmask_b32_e32 v176, v177, v0, vcc
	v_max_f32_e32 v14, 0xe0ad78ec, v176
	s_waitcnt lgkmcnt(13)
	v_mfma_f32_32x32x16_bf16 v[96:111], v[224:227], v[120:123], v[96:111]
	s_cbranch_vccz .Lfast_win_nr_s3
	v_sub_f32_e32 v177, v177, v176
	v_exp_f32_e32 v12, v177
	s_nop 0
	v_mul_f32_e32 v175, v175, v12
	v_pk_mul_f32 v[94:95], v[94:95], v[12:13] op_sel_hi:[1,0]
	v_pk_mul_f32 v[92:93], v[92:93], v[12:13] op_sel_hi:[1,0]
	v_pk_mul_f32 v[90:91], v[90:91], v[12:13] op_sel_hi:[1,0]
	v_pk_mul_f32 v[88:89], v[88:89], v[12:13] op_sel_hi:[1,0]
	v_pk_mul_f32 v[86:87], v[86:87], v[12:13] op_sel_hi:[1,0]
	v_pk_mul_f32 v[84:85], v[84:85], v[12:13] op_sel_hi:[1,0]
	v_pk_mul_f32 v[82:83], v[82:83], v[12:13] op_sel_hi:[1,0]
	v_pk_mul_f32 v[80:81], v[80:81], v[12:13] op_sel_hi:[1,0]
	v_pk_mul_f32 v[78:79], v[78:79], v[12:13] op_sel_hi:[1,0]
	v_pk_mul_f32 v[76:77], v[76:77], v[12:13] op_sel_hi:[1,0]
	v_pk_mul_f32 v[74:75], v[74:75], v[12:13] op_sel_hi:[1,0]
	v_pk_mul_f32 v[72:73], v[72:73], v[12:13] op_sel_hi:[1,0]
	v_pk_mul_f32 v[70:71], v[70:71], v[12:13] op_sel_hi:[1,0]
	v_pk_mul_f32 v[68:69], v[68:69], v[12:13] op_sel_hi:[1,0]
	v_pk_mul_f32 v[66:67], v[66:67], v[12:13] op_sel_hi:[1,0]
	v_pk_mul_f32 v[64:65], v[64:65], v[12:13] op_sel_hi:[1,0]
	v_pk_mul_f32 v[62:63], v[62:63], v[12:13] op_sel_hi:[1,0]
	v_pk_mul_f32 v[60:61], v[60:61], v[12:13] op_sel_hi:[1,0]
	v_pk_mul_f32 v[58:59], v[58:59], v[12:13] op_sel_hi:[1,0]
	v_pk_mul_f32 v[56:57], v[56:57], v[12:13] op_sel_hi:[1,0]
	v_pk_mul_f32 v[54:55], v[54:55], v[12:13] op_sel_hi:[1,0]
	v_pk_mul_f32 v[52:53], v[52:53], v[12:13] op_sel_hi:[1,0]
	v_pk_mul_f32 v[50:51], v[50:51], v[12:13] op_sel_hi:[1,0]
	v_pk_mul_f32 v[48:49], v[48:49], v[12:13] op_sel_hi:[1,0]
	v_pk_mul_f32 v[46:47], v[46:47], v[12:13] op_sel_hi:[1,0]
	v_pk_mul_f32 v[44:45], v[44:45], v[12:13] op_sel_hi:[1,0]
	v_pk_mul_f32 v[42:43], v[42:43], v[12:13] op_sel_hi:[1,0]
	v_pk_mul_f32 v[40:41], v[40:41], v[12:13] op_sel_hi:[1,0]
	v_pk_mul_f32 v[38:39], v[38:39], v[12:13] op_sel_hi:[1,0]
	v_pk_mul_f32 v[36:37], v[36:37], v[12:13] op_sel_hi:[1,0]
	v_pk_mul_f32 v[34:35], v[34:35], v[12:13] op_sel_hi:[1,0]
	v_pk_mul_f32 v[32:33], v[32:33], v[12:13] op_sel_hi:[1,0]
